# v1 + peeled first K-iteration with SrcC=0 (no accumulator zeroing)
# speedup vs baseline: 1.0048x; 1.0048x over previous
.LBB0_177:
	s_add_u32 s0, s14, 0x80
	s_addc_u32 s1, s15, 0
	s_add_u32 s42, s44, 0x100
	s_addc_u32 s43, s45, 0
	s_mov_b32 s14, 0
	v_add_u32_e32 v248, 0x10000, v234
	v_add_u32_e32 v242, s64, v0
	v_add_u32_e32 v249, s64, v176
	v_add_u32_e32 v204, 0x80, v0
	v_add_u32_e32 v205, 0x80, v176
	v_add_u32_e32 v220, 0x80, v172
	v_add_u32_e32 v221, 0x80, v174
	v_add_u32_e32 v218, 0x80, v242
	v_add_u32_e32 v219, 0x80, v249
	s_waitcnt vmcnt(0)
.Lk_peel:
	s_add_i32 s44, s14, 2
	s_add_u32 s45, s0, 0x80
	s_addc_u32 s15, s1, 0
	s_add_i32 s57, 0, 0x10000
	s_cmp_eq_u32 s18, s14
	s_cselect_b32 s15, s89, s15
	s_cselect_b32 s14, s88, s45
	s_cselect_b32 vcc_hi, s11, s43
	s_cselect_b32 vcc_lo, s10, s42
	s_add_i32 s45, 0, 0x14000
	s_waitcnt lgkmcnt(0)
	ds_read_b128 v[130:133], v248
	ds_read_b128 v[134:137], v248 offset:1024
	ds_read_b128 v[138:141], v248 offset:2048
	ds_read_b128 v[142:145], v248 offset:3072
	ds_read_b128 v[146:149], v248 offset:16384
	ds_read_b128 v[150:153], v248 offset:17408
	ds_read_b128 v[154:157], v248 offset:18432
	ds_read_b128 v[158:161], v248 offset:19456
	s_add_i32 m0, s70, 0xc000
	ds_read_b128 v[162:165], v237
	ds_read_b128 v[166:169], v237 offset:1024
	ds_read_b128 v[184:187], v237 offset:2048
	ds_read_b128 v[188:191], v237 offset:3072
	ds_read_b128 v[192:195], v237 offset:4096
	ds_read_b128 v[196:199], v237 offset:5120
	ds_read_b128 v[200:203], v237 offset:6144
	ds_read_b128 v[214:217], v237 offset:7168
	global_load_lds_dwordx4 v180, s[0:1]
	s_add_i32 m0, s70, 0xe000
	s_nop 0
	global_load_lds_dwordx4 v182, s[0:1]
	s_waitcnt vmcnt(8)
	s_waitcnt lgkmcnt(0)
	s_barrier
	s_setprio 1
	s_waitcnt lgkmcnt(0)
	v_mfma_f32_16x16x32_bf16 v[122:125], v[130:133], v[162:165], 0
	v_mfma_f32_16x16x32_bf16 v[126:129], v[138:141], v[162:165], 0
	v_mfma_f32_16x16x32_bf16 v[106:109], v[130:133], v[184:187], 0
	v_mfma_f32_16x16x32_bf16 v[110:113], v[138:141], v[184:187], 0
	v_mfma_f32_16x16x32_bf16 v[90:93], v[130:133], v[192:195], 0
	v_mfma_f32_16x16x32_bf16 v[94:97], v[138:141], v[192:195], 0
	v_mfma_f32_16x16x32_bf16 v[74:77], v[130:133], v[200:203], 0
	v_mfma_f32_16x16x32_bf16 v[78:81], v[138:141], v[200:203], 0
	v_mfma_f32_16x16x32_bf16 v[122:125], v[134:137], v[166:169], v[122:125]
	v_mfma_f32_16x16x32_bf16 v[126:129], v[142:145], v[166:169], v[126:129]
	v_mfma_f32_16x16x32_bf16 v[106:109], v[134:137], v[188:191], v[106:109]
	v_mfma_f32_16x16x32_bf16 v[110:113], v[142:145], v[188:191], v[110:113]
	v_mfma_f32_16x16x32_bf16 v[90:93], v[134:137], v[196:199], v[90:93]
	v_mfma_f32_16x16x32_bf16 v[94:97], v[142:145], v[196:199], v[94:97]
	v_mfma_f32_16x16x32_bf16 v[74:77], v[134:137], v[214:217], v[74:77]
	v_mfma_f32_16x16x32_bf16 v[78:81], v[142:145], v[214:217], v[78:81]
	s_setprio 0
	s_setprio 1
	v_mfma_f32_16x16x32_bf16 v[114:117], v[146:149], v[162:165], 0
	v_mfma_f32_16x16x32_bf16 v[118:121], v[154:157], v[162:165], 0
	v_mfma_f32_16x16x32_bf16 v[98:101], v[146:149], v[184:187], 0
	v_mfma_f32_16x16x32_bf16 v[102:105], v[154:157], v[184:187], 0
	v_mfma_f32_16x16x32_bf16 v[82:85], v[146:149], v[192:195], 0
	v_mfma_f32_16x16x32_bf16 v[86:89], v[154:157], v[192:195], 0
	v_mfma_f32_16x16x32_bf16 v[66:69], v[146:149], v[200:203], 0
	v_mfma_f32_16x16x32_bf16 v[70:73], v[154:157], v[200:203], 0
	v_mfma_f32_16x16x32_bf16 v[114:117], v[150:153], v[166:169], v[114:117]
	v_mfma_f32_16x16x32_bf16 v[118:121], v[158:161], v[166:169], v[118:121]
	v_mfma_f32_16x16x32_bf16 v[98:101], v[150:153], v[188:191], v[98:101]
	v_mfma_f32_16x16x32_bf16 v[102:105], v[158:161], v[188:191], v[102:105]
	v_mfma_f32_16x16x32_bf16 v[82:85], v[150:153], v[196:199], v[82:85]
	v_mfma_f32_16x16x32_bf16 v[86:89], v[158:161], v[196:199], v[86:89]
	v_mfma_f32_16x16x32_bf16 v[66:69], v[150:153], v[214:217], v[66:69]
	v_mfma_f32_16x16x32_bf16 v[70:73], v[158:161], v[214:217], v[70:73]
	s_setprio 0
	s_barrier
	s_add_i32 s57, s57, s59
	s_mov_b32 m0, s57
	ds_read_b128 v[162:165], v237 offset:16384
	ds_read_b128 v[166:169], v237 offset:17408
	ds_read_b128 v[184:187], v237 offset:18432
	ds_read_b128 v[188:191], v237 offset:19456
	ds_read_b128 v[192:195], v237 offset:20480
	ds_read_b128 v[196:199], v237 offset:21504
	ds_read_b128 v[200:203], v237 offset:22528
	ds_read_b128 v[214:217], v237 offset:23552
	global_load_lds_dwordx4 v0, vcc
	s_add_i32 m0, s57, 0x2000
	s_add_i32 s45, s45, s59
	global_load_lds_dwordx4 v176, vcc
	s_mov_b32 m0, s45
	s_nop 0
	global_load_lds_dwordx4 v242, vcc
	s_add_i32 m0, s45, 0x2000
	s_nop 0
	global_load_lds_dwordx4 v249, vcc
	s_mov_b32 m0, s70
	s_nop 0
	global_load_lds_dwordx4 v172, s[14:15]
	s_mov_b32 m0, s4
	s_nop 0
	global_load_lds_dwordx4 v174, s[14:15]
	s_waitcnt vmcnt(8)
	s_waitcnt lgkmcnt(0)
	s_barrier
	s_setprio 1
	s_waitcnt lgkmcnt(0)
	v_mfma_f32_16x16x32_bf16 v[58:61], v[130:133], v[162:165], 0
	v_mfma_f32_16x16x32_bf16 v[62:65], v[138:141], v[162:165], 0
	v_mfma_f32_16x16x32_bf16 v[42:45], v[130:133], v[184:187], 0
	v_mfma_f32_16x16x32_bf16 v[46:49], v[138:141], v[184:187], 0
	v_mfma_f32_16x16x32_bf16 v[26:29], v[130:133], v[192:195], 0
	v_mfma_f32_16x16x32_bf16 v[30:33], v[138:141], v[192:195], 0
	v_mfma_f32_16x16x32_bf16 v[10:13], v[130:133], v[200:203], 0
	v_mfma_f32_16x16x32_bf16 v[14:17], v[138:141], v[200:203], 0
	v_mfma_f32_16x16x32_bf16 v[58:61], v[134:137], v[166:169], v[58:61]
	v_mfma_f32_16x16x32_bf16 v[62:65], v[142:145], v[166:169], v[62:65]
	v_mfma_f32_16x16x32_bf16 v[42:45], v[134:137], v[188:191], v[42:45]
	v_mfma_f32_16x16x32_bf16 v[46:49], v[142:145], v[188:191], v[46:49]
	v_mfma_f32_16x16x32_bf16 v[26:29], v[134:137], v[196:199], v[26:29]
	v_mfma_f32_16x16x32_bf16 v[30:33], v[142:145], v[196:199], v[30:33]
	v_mfma_f32_16x16x32_bf16 v[10:13], v[134:137], v[214:217], v[10:13]
	v_mfma_f32_16x16x32_bf16 v[14:17], v[142:145], v[214:217], v[14:17]
	s_setprio 0
	s_setprio 1
	v_mfma_f32_16x16x32_bf16 v[50:53], v[146:149], v[162:165], 0
	v_mfma_f32_16x16x32_bf16 v[54:57], v[154:157], v[162:165], 0
	v_mfma_f32_16x16x32_bf16 v[34:37], v[146:149], v[184:187], 0
	v_mfma_f32_16x16x32_bf16 v[38:41], v[154:157], v[184:187], 0
	v_mfma_f32_16x16x32_bf16 v[18:21], v[146:149], v[192:195], 0
	v_mfma_f32_16x16x32_bf16 v[22:25], v[154:157], v[192:195], 0
	v_mfma_f32_16x16x32_bf16 v[6:9], v[146:149], v[200:203], 0
	v_mfma_f32_16x16x32_bf16 v[2:5], v[154:157], v[200:203], 0
	v_mfma_f32_16x16x32_bf16 v[50:53], v[150:153], v[166:169], v[50:53]
	v_mfma_f32_16x16x32_bf16 v[54:57], v[158:161], v[166:169], v[54:57]
	v_mfma_f32_16x16x32_bf16 v[34:37], v[150:153], v[188:191], v[34:37]
	v_mfma_f32_16x16x32_bf16 v[38:41], v[158:161], v[188:191], v[38:41]
	v_mfma_f32_16x16x32_bf16 v[18:21], v[150:153], v[196:199], v[18:21]
	v_mfma_f32_16x16x32_bf16 v[22:25], v[158:161], v[196:199], v[22:25]
	v_mfma_f32_16x16x32_bf16 v[6:9], v[150:153], v[214:217], v[6:9]
	v_mfma_f32_16x16x32_bf16 v[2:5], v[158:161], v[214:217], v[2:5]
	s_setprio 0
	s_barrier
	s_add_i32 s45, 0, 0x18000
	s_add_i32 s57, 0, 0x1c000
	ds_read_b128 v[130:133], v248 offset:32768
	ds_read_b128 v[134:137], v248 offset:33792
	ds_read_b128 v[138:141], v248 offset:34816
	ds_read_b128 v[142:145], v248 offset:35840
	ds_read_b128 v[146:149], v248 offset:49152
	ds_read_b128 v[150:153], v248 offset:50176
	ds_read_b128 v[154:157], v248 offset:51200
	ds_read_b128 v[158:161], v248 offset:52224
	s_mov_b32 m0, s63
	ds_read_b128 v[162:165], v237 offset:32768
	ds_read_b128 v[166:169], v237 offset:33792
	ds_read_b128 v[184:187], v237 offset:34816
	ds_read_b128 v[188:191], v237 offset:35840
	ds_read_b128 v[192:195], v237 offset:36864
	ds_read_b128 v[196:199], v237 offset:37888
	ds_read_b128 v[200:203], v237 offset:38912
	ds_read_b128 v[214:217], v237 offset:39936
	global_load_lds_dwordx4 v180, s[14:15]
	s_mov_b32 m0, s68
	s_nop 0
	global_load_lds_dwordx4 v182, s[14:15]
	s_waitcnt vmcnt(8)
	s_waitcnt lgkmcnt(0)
	s_barrier
	s_setprio 1
	s_waitcnt lgkmcnt(0)
	v_mfma_f32_16x16x32_bf16 v[122:125], v[130:133], v[162:165], v[122:125]
	v_mfma_f32_16x16x32_bf16 v[126:129], v[138:141], v[162:165], v[126:129]
	v_mfma_f32_16x16x32_bf16 v[106:109], v[130:133], v[184:187], v[106:109]
	v_mfma_f32_16x16x32_bf16 v[110:113], v[138:141], v[184:187], v[110:113]
	v_mfma_f32_16x16x32_bf16 v[90:93], v[130:133], v[192:195], v[90:93]
	v_mfma_f32_16x16x32_bf16 v[94:97], v[138:141], v[192:195], v[94:97]
	v_mfma_f32_16x16x32_bf16 v[74:77], v[130:133], v[200:203], v[74:77]
	v_mfma_f32_16x16x32_bf16 v[78:81], v[138:141], v[200:203], v[78:81]
	v_mfma_f32_16x16x32_bf16 v[122:125], v[134:137], v[166:169], v[122:125]
	v_mfma_f32_16x16x32_bf16 v[126:129], v[142:145], v[166:169], v[126:129]
	v_mfma_f32_16x16x32_bf16 v[106:109], v[134:137], v[188:191], v[106:109]
	v_mfma_f32_16x16x32_bf16 v[110:113], v[142:145], v[188:191], v[110:113]
	v_mfma_f32_16x16x32_bf16 v[90:93], v[134:137], v[196:199], v[90:93]
	v_mfma_f32_16x16x32_bf16 v[94:97], v[142:145], v[196:199], v[94:97]
	v_mfma_f32_16x16x32_bf16 v[74:77], v[134:137], v[214:217], v[74:77]
	v_mfma_f32_16x16x32_bf16 v[78:81], v[142:145], v[214:217], v[78:81]
	s_setprio 0
	s_setprio 1
	v_mfma_f32_16x16x32_bf16 v[114:117], v[146:149], v[162:165], v[114:117]
	v_mfma_f32_16x16x32_bf16 v[118:121], v[154:157], v[162:165], v[118:121]
	v_mfma_f32_16x16x32_bf16 v[98:101], v[146:149], v[184:187], v[98:101]
	v_mfma_f32_16x16x32_bf16 v[102:105], v[154:157], v[184:187], v[102:105]
	v_mfma_f32_16x16x32_bf16 v[82:85], v[146:149], v[192:195], v[82:85]
	v_mfma_f32_16x16x32_bf16 v[86:89], v[154:157], v[192:195], v[86:89]
	v_mfma_f32_16x16x32_bf16 v[66:69], v[146:149], v[200:203], v[66:69]
	v_mfma_f32_16x16x32_bf16 v[70:73], v[154:157], v[200:203], v[70:73]
	v_mfma_f32_16x16x32_bf16 v[114:117], v[150:153], v[166:169], v[114:117]
	v_mfma_f32_16x16x32_bf16 v[118:121], v[158:161], v[166:169], v[118:121]
	v_mfma_f32_16x16x32_bf16 v[98:101], v[150:153], v[188:191], v[98:101]
	v_mfma_f32_16x16x32_bf16 v[102:105], v[158:161], v[188:191], v[102:105]
	v_mfma_f32_16x16x32_bf16 v[82:85], v[150:153], v[196:199], v[82:85]
	v_mfma_f32_16x16x32_bf16 v[86:89], v[158:161], v[196:199], v[86:89]
	v_mfma_f32_16x16x32_bf16 v[66:69], v[150:153], v[214:217], v[66:69]
	v_mfma_f32_16x16x32_bf16 v[70:73], v[158:161], v[214:217], v[70:73]
	s_setprio 0
	s_barrier
	s_add_i32 m0, s45, s59
	ds_read_b128 v[162:165], v237 offset:49152
	ds_read_b128 v[166:169], v237 offset:50176
	ds_read_b128 v[184:187], v237 offset:51200
	ds_read_b128 v[188:191], v237 offset:52224
	ds_read_b128 v[192:195], v237 offset:53248
	ds_read_b128 v[196:199], v237 offset:54272
	ds_read_b128 v[200:203], v237 offset:55296
	ds_read_b128 v[214:217], v237 offset:56320
	global_load_lds_dwordx4 v204, vcc
	s_add_i32 m0, m0, 0x2000
	s_nop 0
	global_load_lds_dwordx4 v205, vcc
	s_add_i32 m0, s57, s59
	s_nop 0
	global_load_lds_dwordx4 v218, vcc
	s_add_i32 m0, m0, 0x2000
	s_nop 0
	global_load_lds_dwordx4 v219, vcc
	s_mov_b32 m0, s67
	s_nop 0
	global_load_lds_dwordx4 v220, s[14:15]
	s_mov_b32 m0, s7
	s_nop 0
	global_load_lds_dwordx4 v221, s[14:15]
	s_waitcnt vmcnt(8)
	s_waitcnt lgkmcnt(0)
	s_barrier
	s_setprio 1
	s_waitcnt lgkmcnt(0)
	v_mfma_f32_16x16x32_bf16 v[58:61], v[130:133], v[162:165], v[58:61]
	v_mfma_f32_16x16x32_bf16 v[62:65], v[138:141], v[162:165], v[62:65]
	v_mfma_f32_16x16x32_bf16 v[42:45], v[130:133], v[184:187], v[42:45]
	v_mfma_f32_16x16x32_bf16 v[46:49], v[138:141], v[184:187], v[46:49]
	v_mfma_f32_16x16x32_bf16 v[26:29], v[130:133], v[192:195], v[26:29]
	v_mfma_f32_16x16x32_bf16 v[30:33], v[138:141], v[192:195], v[30:33]
	v_mfma_f32_16x16x32_bf16 v[10:13], v[130:133], v[200:203], v[10:13]
	v_mfma_f32_16x16x32_bf16 v[14:17], v[138:141], v[200:203], v[14:17]
	v_mfma_f32_16x16x32_bf16 v[58:61], v[134:137], v[166:169], v[58:61]
	v_mfma_f32_16x16x32_bf16 v[62:65], v[142:145], v[166:169], v[62:65]
	v_mfma_f32_16x16x32_bf16 v[42:45], v[134:137], v[188:191], v[42:45]
	v_mfma_f32_16x16x32_bf16 v[46:49], v[142:145], v[188:191], v[46:49]
	v_mfma_f32_16x16x32_bf16 v[26:29], v[134:137], v[196:199], v[26:29]
	v_mfma_f32_16x16x32_bf16 v[30:33], v[142:145], v[196:199], v[30:33]
	v_mfma_f32_16x16x32_bf16 v[10:13], v[134:137], v[214:217], v[10:13]
	v_mfma_f32_16x16x32_bf16 v[14:17], v[142:145], v[214:217], v[14:17]
	s_setprio 0
	s_setprio 1
	v_mfma_f32_16x16x32_bf16 v[50:53], v[146:149], v[162:165], v[50:53]
	v_mfma_f32_16x16x32_bf16 v[54:57], v[154:157], v[162:165], v[54:57]
	v_mfma_f32_16x16x32_bf16 v[34:37], v[146:149], v[184:187], v[34:37]
	v_mfma_f32_16x16x32_bf16 v[38:41], v[154:157], v[184:187], v[38:41]
	v_mfma_f32_16x16x32_bf16 v[18:21], v[146:149], v[192:195], v[18:21]
	v_mfma_f32_16x16x32_bf16 v[22:25], v[154:157], v[192:195], v[22:25]
	v_mfma_f32_16x16x32_bf16 v[6:9], v[146:149], v[200:203], v[6:9]
	v_mfma_f32_16x16x32_bf16 v[2:5], v[154:157], v[200:203], v[2:5]
	v_mfma_f32_16x16x32_bf16 v[50:53], v[150:153], v[166:169], v[50:53]
	v_mfma_f32_16x16x32_bf16 v[54:57], v[158:161], v[166:169], v[54:57]
	v_mfma_f32_16x16x32_bf16 v[34:37], v[150:153], v[188:191], v[34:37]
	v_mfma_f32_16x16x32_bf16 v[38:41], v[158:161], v[188:191], v[38:41]
	v_mfma_f32_16x16x32_bf16 v[18:21], v[150:153], v[196:199], v[18:21]
	v_mfma_f32_16x16x32_bf16 v[22:25], v[158:161], v[196:199], v[22:25]
	v_mfma_f32_16x16x32_bf16 v[6:9], v[150:153], v[214:217], v[6:9]
	v_mfma_f32_16x16x32_bf16 v[2:5], v[158:161], v[214:217], v[2:5]
	s_setprio 0
	s_barrier
	s_add_u32 s0, s0, 0x100
	s_addc_u32 s1, s1, 0
	s_add_u32 s42, s42, 0x100
	s_addc_u32 s43, s43, 0
	s_cmp_ge_u32 s44, s61
	s_mov_b32 s14, s44
	s_cbranch_scc1 .Lk_exit

.Lk_exit:
	s_and_b64 vcc, exec, s[84:85]
	s_cbranch_vccz .LBB0_181
	s_barrier
